# v23 + moba_merge: all four partial rows requested together; prep: b_re/b_im values for the S5 discretisation requested together instead of 15 dependent pairs
# speedup vs baseline: 1.0279x; 1.0084x over previous
.LBB0_21:
	s_or_b64 exec, exec, s[4:5]
	s_waitcnt vmcnt(0)
	v_mul_f32_e32 v7, v7, v4
	s_mov_b32 s4, 0x3fb8aa3b
	v_mul_f32_e32 v10, 0x3fb8aa3b, v7
	v_fma_f32 v13, v7, s4, -v10
	v_rndne_f32_e32 v14, v10
	v_fmamk_f32 v13, v7, 0x32a5705f, v13
	v_sub_f32_e32 v10, v10, v14
	v_add_f32_e32 v10, v10, v13
	v_exp_f32_e32 v10, v10
	v_cvt_i32_f32_e32 v13, v14
	s_mov_b32 s4, 0xc2ce8ed0
	v_cmp_ngt_f32_e32 vcc, s4, v7
	s_mov_b32 s4, 0x42b17218
	v_ldexp_f32 v10, v10, v13
	v_cndmask_b32_e32 v10, 0, v10, vcc
	v_mov_b32_e32 v13, 0x7f800000
	v_cmp_nlt_f32_e32 vcc, s4, v7
	v_mul_f32_e32 v7, v9, v9
	s_brev_b32 s4, 1
	v_cndmask_b32_e32 v13, v13, v10, vcc
	v_mov_b32_e32 v10, 0x3c0881c4
	v_fmamk_f32 v14, v7, 0xb94c1982, v10
	v_fmaak_f32 v14, v7, v14, 0xbe2aaa9d
	v_mul_f32_e32 v14, v7, v14
	v_fmac_f32_e32 v9, v9, v14
	v_mov_b32_e32 v14, 0xbab64f3b
	v_fmamk_f32 v16, v7, 0x37d75334, v14
	v_fmaak_f32 v16, v7, v16, 0x3d2aabf7
	v_fmaak_f32 v16, v7, v16, 0xbf000004
	v_fma_f32 v7, v7, v16, 1.0
	v_and_b32_e32 v16, 1, v8
	v_cmp_eq_u32_e32 vcc, 0, v16
	v_lshlrev_b32_e32 v8, 30, v8
	v_mov_b32_e32 v15, 0xbe2aaa9d
	v_cndmask_b32_e64 v7, -v9, v7, vcc
	v_bitop3_b32 v7, v8, v7, s4 bitop3:0x6c
	s_movk_i32 s4, 0x1f8
	v_mov_b32_e32 v9, 0x7fc00000
	v_cmp_class_f32_e64 vcc, v5, s4
	v_mov_b32_e32 v17, 0x3d2aabf7
	v_mov_b32_e32 v18, 0xbf000004
	v_cndmask_b32_e32 v16, v9, v7, vcc
	v_mul_f32_e32 v7, v12, v12
	v_fmac_f32_e32 v10, 0xb94c1982, v7
	v_fmac_f32_e32 v15, v7, v10
	v_mul_f32_e32 v10, v7, v15
	v_fmac_f32_e32 v14, 0x37d75334, v7
	v_fmac_f32_e32 v12, v12, v10
	v_fmac_f32_e32 v17, v7, v14
	v_and_b32_e32 v10, 1, v11
	v_fmac_f32_e32 v18, v7, v17
	v_cmp_eq_u32_e64 s[4:5], 0, v10
	v_lshlrev_b32_e32 v10, 30, v11
	v_fma_f32 v7, v7, v18, 1.0
	v_and_b32_e32 v10, 0x80000000, v10
	v_xor_b32_e32 v5, v6, v5
	v_cndmask_b32_e64 v7, v7, v12, s[4:5]
	v_xor_b32_e32 v5, v5, v10
	v_lshlrev_b32_e32 v6, 1, v2
	v_xor_b32_e32 v5, v5, v7
	v_ashrrev_i32_e32 v7, 31, v6
	v_cndmask_b32_e32 v5, v9, v5, vcc
	v_lshl_add_u64 v[6:7], v[6:7], 2, s[88:89]
	s_mov_b32 s4, 0x3d02000
	v_mul_f32_e32 v9, v13, v5
	v_add_co_u32_e32 v10, vcc, s4, v6
	v_mul_f32_e32 v8, v13, v16
	s_nop 0
	v_addc_co_u32_e32 v11, vcc, 0, v7, vcc
	v_mul_f32_e32 v5, v9, v9
	global_store_dwordx2 v[10:11], v[8:9], off sc0 sc1
	v_fma_f32 v5, v8, v8, -v5
	v_add_f32_e32 v8, v8, v8
	v_mul_f32_e32 v8, v8, v9
	v_mul_f32_e32 v10, v8, v8
	v_fma_f32 v10, v5, v5, -v10
	v_add_f32_e32 v5, v5, v5
	v_mul_f32_e32 v5, v8, v5
	v_mul_f32_e32 v8, v5, v5
	v_fma_f32 v8, v10, v10, -v8
	v_add_f32_e32 v10, v10, v10
	v_mul_f32_e32 v5, v5, v10
	v_mul_f32_e32 v10, v5, v5
	v_fma_f32 v10, v8, v8, -v10
	v_add_f32_e32 v8, v8, v8
	v_mul_f32_e32 v5, v5, v8
	v_mul_f32_e32 v8, v5, v5
	v_fma_f32 v8, v10, v10, -v8
	v_add_f32_e32 v10, v10, v10
	v_mul_f32_e32 v5, v5, v10
	v_mul_f32_e32 v10, v5, v5
	s_mov_b32 s4, 0x3d06000
	v_fma_f32 v10, v8, v8, -v10
	v_add_f32_e32 v8, v8, v8
	v_add_co_u32_e32 v6, vcc, s4, v6
	v_mul_f32_e32 v11, v5, v8
	s_nop 0
	v_addc_co_u32_e32 v7, vcc, 0, v7, vcc
	global_store_dwordx2 v[6:7], v[10:11], off sc0 sc1
	v_lshlrev_b32_e32 v6, 4, v2
	v_ashrrev_i32_e32 v7, 31, v6
	v_lshlrev_b64 v[6:7], 2, v[6:7]
	v_lshl_add_u64 v[10:11], s[50:51], 0, v[6:7]
	s_load_dwordx16 s[44:59], s[0:1], 0x40
	v_mul_f32_e32 v5, v1, v1
	v_fma_f32 v13, v13, v16, -1.0
	v_mul_f32_e32 v14, v1, v9
	v_fmac_f32_e32 v14, v4, v13
	s_waitcnt lgkmcnt(0)
	v_lshl_add_u64 v[6:7], s[44:45], 0, v[6:7]
	global_load_dword v8, v[6:7], off
	global_load_dword v12, v[10:11], off
	global_load_dword v60, v[6:7], off offset:4
	global_load_dword v61, v[10:11], off offset:4
	global_load_dword v62, v[6:7], off offset:8
	global_load_dword v63, v[10:11], off offset:8
	global_load_dword v64, v[6:7], off offset:12
	global_load_dword v65, v[10:11], off offset:12
	global_load_dword v66, v[6:7], off offset:16
	global_load_dword v67, v[10:11], off offset:16
	global_load_dword v68, v[6:7], off offset:20
	global_load_dword v69, v[10:11], off offset:20
	global_load_dword v70, v[6:7], off offset:24
	global_load_dword v71, v[10:11], off offset:24
	global_load_dword v72, v[6:7], off offset:28
	global_load_dword v73, v[10:11], off offset:28
	global_load_dword v74, v[6:7], off offset:32
	global_load_dword v75, v[10:11], off offset:32
	global_load_dword v76, v[6:7], off offset:36
	global_load_dword v77, v[10:11], off offset:36
	global_load_dword v78, v[6:7], off offset:40
	global_load_dword v79, v[10:11], off offset:40
	global_load_dword v80, v[6:7], off offset:44
	global_load_dword v81, v[10:11], off offset:44
	global_load_dword v82, v[6:7], off offset:48
	global_load_dword v83, v[10:11], off offset:48
	global_load_dword v84, v[6:7], off offset:52
	global_load_dword v85, v[10:11], off offset:52
	global_load_dword v86, v[6:7], off offset:56
	global_load_dword v87, v[10:11], off offset:56
	global_load_dword v88, v[6:7], off offset:60
	global_load_dword v89, v[10:11], off offset:60
	v_fmac_f32_e32 v5, v4, v4
	v_div_scale_f32 v15, s[4:5], v5, v5, v14
	v_rcp_f32_e32 v16, v15
	v_mul_f32_e32 v1, v1, v13
	v_fma_f32 v1, v4, v9, -v1
	v_lshlrev_b64 v[2:3], 7, v[2:3]
	v_fma_f32 v4, -v15, v16, 1.0
	v_fmac_f32_e32 v16, v4, v16
	v_div_scale_f32 v4, vcc, v14, v5, v14
	v_mul_f32_e32 v9, v4, v16
	v_fma_f32 v13, -v15, v9, v4
	v_fmac_f32_e32 v9, v13, v16
	v_div_scale_f32 v13, s[4:5], v5, v5, v1
	v_fma_f32 v4, -v15, v9, v4
	v_rcp_f32_e32 v15, v13
	v_div_fmas_f32 v4, v4, v16, v9
	v_div_fixup_f32 v9, v4, v5, v14
	v_lshl_add_u64 v[2:3], s[88:89], 0, v[2:3]
	v_fma_f32 v4, -v13, v15, 1.0
	v_fmac_f32_e32 v15, v4, v15
	v_div_scale_f32 v4, vcc, v1, v5, v1
	v_mul_f32_e32 v14, v4, v15
	v_fma_f32 v16, -v13, v14, v4
	v_fmac_f32_e32 v14, v16, v15
	v_fma_f32 v4, -v13, v14, v4
	v_div_fmas_f32 v4, v4, v15, v14
	s_mov_b64 s[4:5], 0x3d0a000
	v_div_fixup_f32 v1, v4, v5, v1
	v_lshl_add_u64 v[4:5], v[2:3], 0, s[4:5]
	s_mov_b32 s4, 0x3d0a000
	v_add_co_u32_e32 v2, vcc, s4, v2
	s_waitcnt vmcnt(31)
	v_mul_f32_e32 v13, v8, v1
	s_waitcnt vmcnt(30)
	v_fma_f32 v13, v12, v9, -v13
	v_addc_co_u32_e32 v3, vcc, 0, v3, vcc
	global_store_dword v[2:3], v13, off sc0 sc1
	v_mul_f32_e32 v2, v8, v9
	v_fmac_f32_e32 v2, v12, v1
	global_store_dword v[4:5], v2, off offset:64 sc0 sc1
	s_waitcnt vmcnt(2)
	v_mov_b32_e32 v2, v60
	v_mov_b32_e32 v3, v61
	v_mul_f32_e32 v8, v2, v1
	v_mul_f32_e32 v2, v2, v9
	v_fma_f32 v8, v3, v9, -v8
	v_fmac_f32_e32 v2, v3, v1
	global_store_dword v[4:5], v8, off offset:4 sc0 sc1
	global_store_dword v[4:5], v2, off offset:68 sc0 sc1
	v_mov_b32_e32 v2, v62
	v_mov_b32_e32 v3, v63
	v_mul_f32_e32 v8, v1, v2
	v_mul_f32_e32 v2, v9, v2
	v_fma_f32 v8, v9, v3, -v8
	v_fmac_f32_e32 v2, v1, v3
	global_store_dword v[4:5], v8, off offset:8 sc0 sc1
	global_store_dword v[4:5], v2, off offset:72 sc0 sc1
	v_mov_b32_e32 v2, v64
	v_mov_b32_e32 v3, v65
	v_mul_f32_e32 v8, v1, v2
	v_mul_f32_e32 v2, v9, v2
	v_fma_f32 v8, v9, v3, -v8
	v_fmac_f32_e32 v2, v1, v3
	global_store_dword v[4:5], v8, off offset:12 sc0 sc1
	global_store_dword v[4:5], v2, off offset:76 sc0 sc1
	v_mov_b32_e32 v2, v66
	v_mov_b32_e32 v3, v67
	v_mul_f32_e32 v8, v1, v2
	v_mul_f32_e32 v2, v9, v2
	v_fma_f32 v8, v9, v3, -v8
	v_fmac_f32_e32 v2, v1, v3
	global_store_dword v[4:5], v8, off offset:16 sc0 sc1
	global_store_dword v[4:5], v2, off offset:80 sc0 sc1
	v_mov_b32_e32 v2, v68
	v_mov_b32_e32 v3, v69
	v_mul_f32_e32 v8, v1, v2
	v_mul_f32_e32 v2, v9, v2
	v_fma_f32 v8, v9, v3, -v8
	v_fmac_f32_e32 v2, v1, v3
	global_store_dword v[4:5], v8, off offset:20 sc0 sc1
	global_store_dword v[4:5], v2, off offset:84 sc0 sc1
	v_mov_b32_e32 v2, v70
	v_mov_b32_e32 v3, v71
	v_mul_f32_e32 v8, v1, v2
	v_mul_f32_e32 v2, v9, v2
	v_fma_f32 v8, v9, v3, -v8
	v_fmac_f32_e32 v2, v1, v3
	global_store_dword v[4:5], v8, off offset:24 sc0 sc1
	global_store_dword v[4:5], v2, off offset:88 sc0 sc1
	v_mov_b32_e32 v2, v72
	v_mov_b32_e32 v3, v73
	v_mul_f32_e32 v8, v1, v2
	v_mul_f32_e32 v2, v9, v2
	v_fma_f32 v8, v9, v3, -v8
	v_fmac_f32_e32 v2, v1, v3
	global_store_dword v[4:5], v8, off offset:28 sc0 sc1
	global_store_dword v[4:5], v2, off offset:92 sc0 sc1
	v_mov_b32_e32 v2, v74
	v_mov_b32_e32 v3, v75
	v_mul_f32_e32 v8, v1, v2
	v_mul_f32_e32 v2, v9, v2
	v_fma_f32 v8, v9, v3, -v8
	v_fmac_f32_e32 v2, v1, v3
	global_store_dword v[4:5], v8, off offset:32 sc0 sc1
	global_store_dword v[4:5], v2, off offset:96 sc0 sc1
	v_mov_b32_e32 v2, v76
	v_mov_b32_e32 v3, v77
	v_mul_f32_e32 v8, v1, v2
	v_mul_f32_e32 v2, v9, v2
	v_fma_f32 v8, v9, v3, -v8
	v_fmac_f32_e32 v2, v1, v3
	global_store_dword v[4:5], v8, off offset:36 sc0 sc1
	global_store_dword v[4:5], v2, off offset:100 sc0 sc1
	v_mov_b32_e32 v2, v78
	v_mov_b32_e32 v3, v79
	v_mul_f32_e32 v8, v1, v2
	v_mul_f32_e32 v2, v9, v2
	v_fma_f32 v8, v9, v3, -v8
	v_fmac_f32_e32 v2, v1, v3
	global_store_dword v[4:5], v8, off offset:40 sc0 sc1
	global_store_dword v[4:5], v2, off offset:104 sc0 sc1
	v_mov_b32_e32 v2, v80
	v_mov_b32_e32 v3, v81
	v_mul_f32_e32 v8, v1, v2
	v_mul_f32_e32 v2, v9, v2
	v_fma_f32 v8, v9, v3, -v8
	v_fmac_f32_e32 v2, v1, v3
	global_store_dword v[4:5], v8, off offset:44 sc0 sc1
	global_store_dword v[4:5], v2, off offset:108 sc0 sc1
	v_mov_b32_e32 v2, v82
	v_mov_b32_e32 v3, v83
	v_mul_f32_e32 v8, v1, v2
	v_mul_f32_e32 v2, v9, v2
	v_fma_f32 v8, v9, v3, -v8
	v_fmac_f32_e32 v2, v1, v3
	global_store_dword v[4:5], v8, off offset:48 sc0 sc1
	global_store_dword v[4:5], v2, off offset:112 sc0 sc1
	v_mov_b32_e32 v2, v84
	v_mov_b32_e32 v3, v85
	v_mul_f32_e32 v8, v1, v2
	v_mul_f32_e32 v2, v9, v2
	v_fma_f32 v8, v9, v3, -v8
	v_fmac_f32_e32 v2, v1, v3
	global_store_dword v[4:5], v8, off offset:52 sc0 sc1
	global_store_dword v[4:5], v2, off offset:116 sc0 sc1
	v_mov_b32_e32 v2, v86
	v_mov_b32_e32 v3, v87
	v_mul_f32_e32 v8, v1, v2
	v_mul_f32_e32 v2, v9, v2
	v_fma_f32 v8, v9, v3, -v8
	v_fmac_f32_e32 v2, v1, v3
	global_store_dword v[4:5], v8, off offset:56 sc0 sc1
	global_store_dword v[4:5], v2, off offset:120 sc0 sc1
	v_mov_b32_e32 v2, v88
	v_mov_b32_e32 v3, v89
	v_mul_f32_e32 v6, v1, v2
	v_mul_f32_e32 v2, v9, v2
	v_fma_f32 v6, v9, v3, -v6
	v_fmac_f32_e32 v2, v1, v3
	global_store_dword v[4:5], v6, off offset:60 sc0 sc1
	global_store_dword v[4:5], v2, off offset:124 sc0 sc1

.LBB0_1532:
	v_lshrrev_b64 v[18:19], 3, v[8:9]
	v_lshlrev_b64 v[0:1], 4, v[18:19]
	v_lshl_add_u64 v[2:3], s[2:3], 0, v[0:1]
	global_load_dwordx4 v[4:7], v[2:3], off
	v_lshlrev_b64 v[2:3], 9, v[18:19]
	v_lshl_add_u64 v[28:29], v[12:13], 0, v[2:3]
	v_lshl_add_u64 v[0:1], s[8:9], 0, v[0:1]
	global_load_dwordx4 v[20:23], v[28:29], off
	global_load_dwordx4 v[40:43], v[28:29], off offset:128
	global_load_dwordx4 v[44:47], v[28:29], off offset:256
	global_load_dwordx4 v[48:51], v[28:29], off offset:384
	s_waitcnt vmcnt(4)
	v_max_f32_e32 v10, v5, v5
	global_load_dwordx4 v[0:3], v[0:1], off
	v_max_f32_e32 v19, v4, v4
	v_max_f32_e32 v10, v19, v10
	v_max_f32_e32 v26, v6, v6
	v_max_f32_e32 v27, v7, v7
	s_waitcnt vmcnt(4)
	v_lshlrev_b32_e32 v24, 16, v20
	v_and_b32_e32 v25, 0xffff0000, v20
	v_lshlrev_b32_e32 v20, 16, v21
	v_and_b32_e32 v21, 0xffff0000, v21
	v_lshlrev_b32_e32 v30, 16, v22
	v_and_b32_e32 v31, 0xffff0000, v22
	v_lshlrev_b32_e32 v32, 16, v23
	v_and_b32_e32 v33, 0xffff0000, v23
	s_waitcnt vmcnt(0)
	v_cmp_lt_f32_e64 s[6:7], 0, v1
	s_nop 1
	v_cndmask_b32_e64 v10, v4, v10, s[6:7]
	v_max_f32_e32 v19, v10, v10
	v_max_f32_e32 v19, v19, v26
	v_cmp_lt_f32_e64 s[0:1], 0, v2
	v_cmp_lt_f32_e32 vcc, 0, v3
	s_nop 0
	v_cndmask_b32_e64 v19, v10, v19, s[0:1]
	v_max_f32_e32 v10, v19, v19
	v_max_f32_e32 v10, v10, v27
	v_cndmask_b32_e32 v19, v19, v10, vcc
	v_sub_f32_e32 v4, v4, v19
	v_mul_f32_e32 v4, 0x3fb8aa3b, v4
	v_exp_f32_e32 v34, v4
	s_nop 0
	v_mul_f32_e32 v4, v0, v34
	v_pk_fma_f32 v[26:27], v[4:5], v[24:25], 0 op_sel_hi:[0,1,0]
	v_pk_fma_f32 v[24:25], v[4:5], v[20:21], 0 op_sel_hi:[0,1,0]
	v_pk_fma_f32 v[22:23], v[4:5], v[30:31], 0 op_sel_hi:[0,1,0]
	v_pk_fma_f32 v[20:21], v[4:5], v[32:33], 0 op_sel_hi:[0,1,0]
	v_fma_f32 v0, v0, v34, 0
	s_and_saveexec_b64 s[20:21], s[6:7]
	s_cbranch_execz .LBB0_1535
	v_sub_f32_e32 v4, v5, v19
	v_mul_f32_e32 v4, 0x3fb8aa3b, v4
	v_exp_f32_e32 v5, v4
	v_lshlrev_b32_e32 v34, 16, v40
	v_mul_f32_e32 v4, v1, v5
	v_and_b32_e32 v35, 0xffff0000, v40
	v_lshlrev_b32_e32 v30, 16, v41
	v_and_b32_e32 v31, 0xffff0000, v41
	v_lshlrev_b32_e32 v36, 16, v42
	v_and_b32_e32 v37, 0xffff0000, v42
	v_lshlrev_b32_e32 v32, 16, v43
	v_and_b32_e32 v33, 0xffff0000, v43
	v_pk_fma_f32 v[20:21], v[4:5], v[32:33], v[20:21] op_sel_hi:[0,1,1]
	v_pk_fma_f32 v[22:23], v[4:5], v[36:37], v[22:23] op_sel_hi:[0,1,1]
	v_pk_fma_f32 v[24:25], v[4:5], v[30:31], v[24:25] op_sel_hi:[0,1,1]
	v_pk_fma_f32 v[26:27], v[4:5], v[34:35], v[26:27] op_sel_hi:[0,1,1]
	v_fmac_f32_e32 v0, v1, v5
	s_or_b64 exec, exec, s[20:21]
	s_and_saveexec_b64 s[6:7], s[0:1]
	s_cbranch_execnz .LBB0_1536

.LBB0_1536:
	v_sub_f32_e32 v1, v6, v19
	v_mul_f32_e32 v1, 0x3fb8aa3b, v1
	v_exp_f32_e32 v1, v1
	v_lshlrev_b32_e32 v34, 16, v44
	v_mul_f32_e32 v4, v2, v1
	v_and_b32_e32 v35, 0xffff0000, v44
	v_lshlrev_b32_e32 v30, 16, v45
	v_and_b32_e32 v31, 0xffff0000, v45
	v_lshlrev_b32_e32 v36, 16, v46
	v_and_b32_e32 v37, 0xffff0000, v46
	v_lshlrev_b32_e32 v32, 16, v47
	v_and_b32_e32 v33, 0xffff0000, v47
	v_pk_fma_f32 v[20:21], v[4:5], v[32:33], v[20:21] op_sel_hi:[0,1,1]
	v_pk_fma_f32 v[22:23], v[4:5], v[36:37], v[22:23] op_sel_hi:[0,1,1]
	v_pk_fma_f32 v[24:25], v[4:5], v[30:31], v[24:25] op_sel_hi:[0,1,1]
	v_pk_fma_f32 v[26:27], v[4:5], v[34:35], v[26:27] op_sel_hi:[0,1,1]
	v_fmac_f32_e32 v0, v2, v1
	s_or_b64 exec, exec, s[6:7]
	s_and_saveexec_b64 s[0:1], vcc
	s_cbranch_execz .LBB0_1531
.LBB0_1537:
	v_sub_f32_e32 v1, v7, v10
	v_mul_f32_e32 v1, 0x3fb8aa3b, v1
	v_exp_f32_e32 v1, v1
	v_lshlrev_b32_e32 v4, 16, v48
	v_mul_f32_e32 v2, v3, v1
	v_and_b32_e32 v5, 0xffff0000, v48
	v_lshlrev_b32_e32 v6, 16, v49
	v_and_b32_e32 v7, 0xffff0000, v49
	v_lshlrev_b32_e32 v28, 16, v50
	v_and_b32_e32 v29, 0xffff0000, v50
	v_lshlrev_b32_e32 v30, 16, v51
	v_and_b32_e32 v31, 0xffff0000, v51
	v_pk_fma_f32 v[20:21], v[2:3], v[30:31], v[20:21] op_sel_hi:[0,1,1]
	v_pk_fma_f32 v[22:23], v[2:3], v[28:29], v[22:23] op_sel_hi:[0,1,1]
	v_pk_fma_f32 v[24:25], v[2:3], v[6:7], v[24:25] op_sel_hi:[0,1,1]
	v_pk_fma_f32 v[26:27], v[2:3], v[4:5], v[26:27] op_sel_hi:[0,1,1]
	v_fmac_f32_e32 v0, v3, v1
	s_branch .LBB0_1531
